# G1 K-loop: 7 of 16 LDS-DMA loads use SGPR-base addressing (no 64-bit VALU address add)
# baseline (speedup 1.0000x reference)
; #define PG8_STAGE(bufoff, gbase, voff) do { _Pragma("unroll") for (int _i = 0; _i < 2; ++_i) \
;         __builtin_amdgcn_global_load_lds((const unsigned*)((const char*)(gbase) + (voff)[_i]), (LAS unsigned*)(lds + (bufoff) + ldsw + _i * 8192), 16, 0, 0); } while (0)
; #define PG8_LDA(dst, b, h) do { _Pragma("unroll") for (int m = 0; m < 4; ++m) _Pragma("unroll") for (int k = 0; k < 2; ++k) dst[m][k] = *(const LAS bf16x8*)(lds + PG8_SA(b, h) + aoff + m * 2048 + k * 1024); } while (0)
; #define PG8_LDB(dst, b, h) do { _Pragma("unroll") for (int n = 0; n < 2; ++n) _Pragma("unroll") for (int k = 0; k < 2; ++k) dst[n][k] = *(const LAS bf16x8*)(lds + PG8_SB(b, h) + boff + n * 2048 + k * 1024); } while (0)
; #define PG8_SCHED __builtin_amdgcn_sched_barrier(0)
; template <class Epi, class Sched, bool ALIGN_EPI = false, bool SP2 = false>
; __device__ __forceinline__ void gemm_phase(LAS unsigned char* lds, const Gemm g, const Sched& S, const Epi& E, const int tid) {
;     ...
;         const char* nA = has_next ? (const char*)g.A + (size_t)nxt.pm * tstep + (size_t)nxt.k0 * kstep : cA; const char* nB = has_next ? (const char*)g.Bt + (size_t)nxt.pn * tstep + (size_t)nxt.k0 * kstep : cB;
;         const int nt = cur.nk;
;         for (int t = 0; t < nt; t += 2) {
;             const bool last = (t == nt - 2);
;             const char* a1 = cA + (size_t)(t + 1) * kstep;
;             const char* a2 = last ? nA : cA + (size_t)(t + 2) * kstep; const char* b2 = last ? nB : cB + (size_t)(t + 2) * kstep;
;             const char* a3 = a2 + kstep; const char* b3 = b2 + kstep;
;             if (last && has_next) S.a_ready(nxt);
;             if constexpr (SP2) {
;             PG8_LDB(B0, 0, 0); PG8_LDB(B1, 0, 1); PG8_SCHED; PG8_LDA(At, 0, 0); PG8_STAGE(PG8_SA(1, 1), a1 + hstep, voffA);
.LBB0_592:
	s_add_u32 s30, s28, 0xfffc0080
	s_addc_u32 s31, s29, -1
	s_add_i32 s55, 0, 0x10000
	s_cmp_eq_u32 s54, 12
	s_cselect_b32 s35, s21, s31
	s_cselect_b32 s34, s50, s30
	v_add_u32_e32 v144, s55, v147
	s_cselect_b32 s31, s13, s53
	s_cselect_b32 s30, s51, s52
	s_add_i32 s57, 0, 0x14000
	ds_read_b128 v[140:143], v144
	ds_read_b128 v[150:153], v144 offset:1024
	ds_read_b128 v[154:157], v144 offset:2048
	ds_read_b128 v[160:163], v144 offset:3072
	v_add_u32_e32 v144, s57, v147
	ds_read_b128 v[164:167], v144
	ds_read_b128 v[168:171], v144 offset:1024
	ds_read_b128 v[172:175], v144 offset:2048
	ds_read_b128 v[176:179], v144 offset:3072

; #define PG8_STAGE(bufoff, gbase, voff) do { _Pragma("unroll") for (int _i = 0; _i < 2; ++_i) \
;         __builtin_amdgcn_global_load_lds((const unsigned*)((const char*)(gbase) + (voff)[_i]), (LAS unsigned*)(lds + (bufoff) + ldsw + _i * 8192), 16, 0, 0); } while (0)
; #define PG8_LDA(dst, b, h) do { _Pragma("unroll") for (int m = 0; m < 4; ++m) _Pragma("unroll") for (int k = 0; k < 2; ++k) dst[m][k] = *(const LAS bf16x8*)(lds + PG8_SA(b, h) + aoff + m * 2048 + k * 1024); } while (0)
; #define PG8_LDB(dst, b, h) do { _Pragma("unroll") for (int n = 0; n < 2; ++n) _Pragma("unroll") for (int k = 0; k < 2; ++k) dst[n][k] = *(const LAS bf16x8*)(lds + PG8_SB(b, h) + boff + n * 2048 + k * 1024); } while (0)
; #define PG8_MMA(ai, bj, At, Bt) do { __builtin_amdgcn_s_setprio(1); _Pragma("unroll") for (int m = 0; m < 4; ++m) _Pragma("unroll") for (int n = 0; n < 2; ++n) _Pragma("unroll") for (int k = 0; k < 2; ++k) \
;         acc[ai][bj][m][n] = __builtin_amdgcn_mfma_f32_16x16x32_bf16(Bt[n][k], At[m][k], acc[ai][bj][m][n], 0, 0, 0); __builtin_amdgcn_s_setprio(0); } while (0)
; #define PG8_WAIT_V(n) asm volatile("s_waitcnt vmcnt(" #n ")" ::: "memory")
; #define PG8_WAIT_L(n) asm volatile("s_waitcnt lgkmcnt(" #n ")" ::: "memory")
; #define PG8_BAR __builtin_amdgcn_s_barrier()
; #define PG8_SCHED __builtin_amdgcn_sched_barrier(0)
; template <class Epi, class Sched, bool ALIGN_EPI = false, bool SP2 = false>
; __device__ __forceinline__ void gemm_phase(LAS unsigned char* lds, const Gemm g, const Sched& S, const Epi& E, const int tid) {
;     ...
;             PG8_LDB(B0, 0, 0); PG8_LDB(B1, 0, 1); PG8_SCHED; PG8_LDA(At, 0, 0); PG8_STAGE(PG8_SA(1, 1), a1 + hstep, voffA);
;             PG8_WAIT_V(8); PG8_WAIT_L(0); PG8_BAR; PG8_MMA(0, 0, At, B0); PG8_MMA(0, 1, At, B1); PG8_BAR; PG8_SCHED;
	s_add_i32 m0, s43, 0xc000
	ds_read_b128 v[180:183], v149
	ds_read_b128 v[208:211], v149 offset:1024
	ds_read_b128 v[212:215], v149 offset:2048
	ds_read_b128 v[216:219], v149 offset:3072
	ds_read_b128 v[220:223], v149 offset:4096
	ds_read_b128 v[224:227], v149 offset:5120
	ds_read_b128 v[228:231], v149 offset:6144
	ds_read_b128 v[232:235], v149 offset:7168
	global_load_lds_dwordx4 v138, s[28:29]

; #define PG8_STAGE(bufoff, gbase, voff) do { _Pragma("unroll") for (int _i = 0; _i < 2; ++_i) \
;         __builtin_amdgcn_global_load_lds((const unsigned*)((const char*)(gbase) + (voff)[_i]), (LAS unsigned*)(lds + (bufoff) + ldsw + _i * 8192), 16, 0, 0); } while (0)
; #define PG8_LDA(dst, b, h) do { _Pragma("unroll") for (int m = 0; m < 4; ++m) _Pragma("unroll") for (int k = 0; k < 2; ++k) dst[m][k] = *(const LAS bf16x8*)(lds + PG8_SA(b, h) + aoff + m * 2048 + k * 1024); } while (0)
; #define PG8_LDB(dst, b, h) do { _Pragma("unroll") for (int n = 0; n < 2; ++n) _Pragma("unroll") for (int k = 0; k < 2; ++k) dst[n][k] = *(const LAS bf16x8*)(lds + PG8_SB(b, h) + boff + n * 2048 + k * 1024); } while (0)
; #define PG8_MMA(ai, bj, At, Bt) do { __builtin_amdgcn_s_setprio(1); _Pragma("unroll") for (int m = 0; m < 4; ++m) _Pragma("unroll") for (int n = 0; n < 2; ++n) _Pragma("unroll") for (int k = 0; k < 2; ++k) \
;         acc[ai][bj][m][n] = __builtin_amdgcn_mfma_f32_16x16x32_bf16(Bt[n][k], At[m][k], acc[ai][bj][m][n], 0, 0, 0); __builtin_amdgcn_s_setprio(0); } while (0)
; #define PG8_WAIT_V(n) asm volatile("s_waitcnt vmcnt(" #n ")" ::: "memory")
; #define PG8_WAIT_L(n) asm volatile("s_waitcnt lgkmcnt(" #n ")" ::: "memory")
; #define PG8_BAR __builtin_amdgcn_s_barrier()
; #define PG8_SCHED __builtin_amdgcn_sched_barrier(0)
; template <class Epi, class Sched, bool ALIGN_EPI = false, bool SP2 = false>
; __device__ __forceinline__ void gemm_phase(LAS unsigned char* lds, const Gemm g, const Sched& S, const Epi& E, const int tid) {
;     ...
;             PG8_LDB(B0, 0, 0); PG8_LDB(B1, 0, 1); PG8_SCHED; PG8_LDA(At, 0, 0); PG8_STAGE(PG8_SA(1, 1), a1 + hstep, voffA);
;             PG8_WAIT_V(8); PG8_WAIT_L(0); PG8_BAR; PG8_MMA(0, 0, At, B0); PG8_MMA(0, 1, At, B1); PG8_BAR; PG8_SCHED;
;             PG8_LDA(At, 0, 1); PG8_STAGE(PG8_SB(0, 0), b2, voffB); PG8_STAGE(PG8_SB(0, 1), b2 + hstep, voffB); PG8_STAGE(PG8_SA(0, 0), a2, voffA);
	s_add_i32 m0, s43, 0xe000
	s_nop 0
	global_load_lds_dwordx4 v136, s[28:29]
	s_waitcnt vmcnt(8)
	s_waitcnt lgkmcnt(0)
	s_barrier
	s_setprio 1
	s_waitcnt lgkmcnt(0)
	v_mfma_f32_16x16x32_bf16 v[126:129], v[140:143], v[180:183], v[126:129]
	v_mfma_f32_16x16x32_bf16 v[118:121], v[154:157], v[180:183], v[118:121]
	v_mfma_f32_16x16x32_bf16 v[110:113], v[140:143], v[212:215], v[110:113]
	v_mfma_f32_16x16x32_bf16 v[102:105], v[154:157], v[212:215], v[102:105]
	v_mfma_f32_16x16x32_bf16 v[94:97], v[140:143], v[220:223], v[94:97]
	v_mfma_f32_16x16x32_bf16 v[86:89], v[154:157], v[220:223], v[86:89]
	v_mfma_f32_16x16x32_bf16 v[78:81], v[140:143], v[228:231], v[78:81]
	v_mfma_f32_16x16x32_bf16 v[70:73], v[154:157], v[228:231], v[70:73]
	v_mfma_f32_16x16x32_bf16 v[126:129], v[150:153], v[208:211], v[126:129]
	v_mfma_f32_16x16x32_bf16 v[118:121], v[160:163], v[208:211], v[118:121]
	v_mfma_f32_16x16x32_bf16 v[110:113], v[150:153], v[216:219], v[110:113]
	v_mfma_f32_16x16x32_bf16 v[102:105], v[160:163], v[216:219], v[102:105]
	v_mfma_f32_16x16x32_bf16 v[94:97], v[150:153], v[224:227], v[94:97]
	v_mfma_f32_16x16x32_bf16 v[86:89], v[160:163], v[224:227], v[86:89]
	v_mfma_f32_16x16x32_bf16 v[78:81], v[150:153], v[232:235], v[78:81]
	v_mfma_f32_16x16x32_bf16 v[70:73], v[160:163], v[232:235], v[70:73]
	s_setprio 0
	s_setprio 1
	v_mfma_f32_16x16x32_bf16 v[122:125], v[164:167], v[180:183], v[122:125]
	v_mfma_f32_16x16x32_bf16 v[114:117], v[172:175], v[180:183], v[114:117]
	v_mfma_f32_16x16x32_bf16 v[106:109], v[164:167], v[212:215], v[106:109]
	v_mfma_f32_16x16x32_bf16 v[98:101], v[172:175], v[212:215], v[98:101]
	v_mfma_f32_16x16x32_bf16 v[90:93], v[164:167], v[220:223], v[90:93]
	v_mfma_f32_16x16x32_bf16 v[82:85], v[172:175], v[220:223], v[82:85]
	v_mfma_f32_16x16x32_bf16 v[74:77], v[164:167], v[228:231], v[74:77]
	v_mfma_f32_16x16x32_bf16 v[66:69], v[172:175], v[228:231], v[66:69]
	v_mfma_f32_16x16x32_bf16 v[122:125], v[168:171], v[208:211], v[122:125]
	v_mfma_f32_16x16x32_bf16 v[114:117], v[176:179], v[208:211], v[114:117]
	v_mfma_f32_16x16x32_bf16 v[106:109], v[168:171], v[216:219], v[106:109]
	v_mfma_f32_16x16x32_bf16 v[98:101], v[176:179], v[216:219], v[98:101]
	v_mfma_f32_16x16x32_bf16 v[90:93], v[168:171], v[224:227], v[90:93]
	v_mfma_f32_16x16x32_bf16 v[82:85], v[176:179], v[224:227], v[82:85]
	v_mfma_f32_16x16x32_bf16 v[74:77], v[168:171], v[232:235], v[74:77]
	v_mfma_f32_16x16x32_bf16 v[66:69], v[176:179], v[232:235], v[66:69]
	s_setprio 0
	s_barrier
	s_add_i32 s55, s55, s40
	v_lshl_add_u64 v[144:145], s[30:31], 0, v[0:1]
	s_mov_b32 m0, s55
	ds_read_b128 v[180:183], v149 offset:16384
	ds_read_b128 v[208:211], v149 offset:17408
	ds_read_b128 v[212:215], v149 offset:18432
	ds_read_b128 v[216:219], v149 offset:19456
	ds_read_b128 v[220:223], v149 offset:20480
	ds_read_b128 v[224:227], v149 offset:21504
	ds_read_b128 v[228:231], v149 offset:22528
	ds_read_b128 v[232:235], v149 offset:23552
	global_load_lds_dwordx4 v[144:145], off
	s_add_i32 m0, s55, 0x2000
	s_add_u32 s60, s30, 0x40000
	v_lshl_add_u64 v[236:237], s[30:31], 0, v[130:131]
	s_addc_u32 s61, s31, 0
	s_add_i32 s55, s57, s40
	global_load_lds_dwordx4 v[236:237], off
	v_lshl_add_u64 v[238:239], s[60:61], 0, v[0:1]
	s_mov_b32 m0, s55
	v_lshl_add_u64 v[240:241], s[34:35], 0, v[132:133]
	global_load_lds_dwordx4 v[238:239], off

; #define PG8_STAGE(bufoff, gbase, voff) do { _Pragma("unroll") for (int _i = 0; _i < 2; ++_i) \
;         __builtin_amdgcn_global_load_lds((const unsigned*)((const char*)(gbase) + (voff)[_i]), (LAS unsigned*)(lds + (bufoff) + ldsw + _i * 8192), 16, 0, 0); } while (0)
; #define PG8_LDA(dst, b, h) do { _Pragma("unroll") for (int m = 0; m < 4; ++m) _Pragma("unroll") for (int k = 0; k < 2; ++k) dst[m][k] = *(const LAS bf16x8*)(lds + PG8_SA(b, h) + aoff + m * 2048 + k * 1024); } while (0)
; #define PG8_LDB(dst, b, h) do { _Pragma("unroll") for (int n = 0; n < 2; ++n) _Pragma("unroll") for (int k = 0; k < 2; ++k) dst[n][k] = *(const LAS bf16x8*)(lds + PG8_SB(b, h) + boff + n * 2048 + k * 1024); } while (0)
; #define PG8_MMA(ai, bj, At, Bt) do { __builtin_amdgcn_s_setprio(1); _Pragma("unroll") for (int m = 0; m < 4; ++m) _Pragma("unroll") for (int n = 0; n < 2; ++n) _Pragma("unroll") for (int k = 0; k < 2; ++k) \
;         acc[ai][bj][m][n] = __builtin_amdgcn_mfma_f32_16x16x32_bf16(Bt[n][k], At[m][k], acc[ai][bj][m][n], 0, 0, 0); __builtin_amdgcn_s_setprio(0); } while (0)
; #define PG8_WAIT_V(n) asm volatile("s_waitcnt vmcnt(" #n ")" ::: "memory")
; #define PG8_WAIT_L(n) asm volatile("s_waitcnt lgkmcnt(" #n ")" ::: "memory")
; #define PG8_BAR __builtin_amdgcn_s_barrier()
; #define PG8_SCHED __builtin_amdgcn_sched_barrier(0)
; template <class Epi, class Sched, bool ALIGN_EPI = false, bool SP2 = false>
; __device__ __forceinline__ void gemm_phase(LAS unsigned char* lds, const Gemm g, const Sched& S, const Epi& E, const int tid) {
;     ...
;             PG8_LDA(At, 0, 1); PG8_STAGE(PG8_SB(0, 0), b2, voffB); PG8_STAGE(PG8_SB(0, 1), b2 + hstep, voffB); PG8_STAGE(PG8_SA(0, 0), a2, voffA);
;             PG8_WAIT_V(8); PG8_WAIT_L(0); PG8_BAR; PG8_MMA(1, 0, At, B0); PG8_MMA(1, 1, At, B1); PG8_BAR; PG8_SCHED;
;             PG8_LDB(B0, 1, 0); PG8_LDB(B1, 1, 1); PG8_SCHED; PG8_LDA(At, 1, 0); PG8_STAGE(PG8_SA(0, 1), a2 + hstep, voffA);
	s_add_i32 m0, s55, 0x2000
	s_nop 0
	global_load_lds_dwordx4 v130, s[60:61]
	v_lshl_add_u64 v[238:239], s[34:35], 0, v[134:135]
	s_mov_b32 m0, s43
	s_nop 0
	global_load_lds_dwordx4 v[238:239], off
	s_mov_b32 m0, s44
	s_nop 0
	global_load_lds_dwordx4 v[240:241], off
	s_waitcnt vmcnt(8)
	s_waitcnt lgkmcnt(0)
	s_barrier
	s_setprio 1
	s_waitcnt lgkmcnt(0)
	v_mfma_f32_16x16x32_bf16 v[62:65], v[140:143], v[180:183], v[62:65]
	v_mfma_f32_16x16x32_bf16 v[54:57], v[154:157], v[180:183], v[54:57]
	v_mfma_f32_16x16x32_bf16 v[46:49], v[140:143], v[212:215], v[46:49]
	v_mfma_f32_16x16x32_bf16 v[38:41], v[154:157], v[212:215], v[38:41]
	v_mfma_f32_16x16x32_bf16 v[30:33], v[140:143], v[220:223], v[30:33]
	v_mfma_f32_16x16x32_bf16 v[22:25], v[154:157], v[220:223], v[22:25]
	v_mfma_f32_16x16x32_bf16 v[14:17], v[140:143], v[228:231], v[14:17]
	v_mfma_f32_16x16x32_bf16 v[6:9], v[154:157], v[228:231], v[6:9]
	v_mfma_f32_16x16x32_bf16 v[62:65], v[150:153], v[208:211], v[62:65]
	v_mfma_f32_16x16x32_bf16 v[54:57], v[160:163], v[208:211], v[54:57]
	v_mfma_f32_16x16x32_bf16 v[46:49], v[150:153], v[216:219], v[46:49]
	v_mfma_f32_16x16x32_bf16 v[38:41], v[160:163], v[216:219], v[38:41]
	v_mfma_f32_16x16x32_bf16 v[30:33], v[150:153], v[224:227], v[30:33]
	v_mfma_f32_16x16x32_bf16 v[22:25], v[160:163], v[224:227], v[22:25]
	v_mfma_f32_16x16x32_bf16 v[14:17], v[150:153], v[232:235], v[14:17]
	v_mfma_f32_16x16x32_bf16 v[6:9], v[160:163], v[232:235], v[6:9]
	s_setprio 0
	s_setprio 1
	v_mfma_f32_16x16x32_bf16 v[58:61], v[164:167], v[180:183], v[58:61]
	v_mfma_f32_16x16x32_bf16 v[50:53], v[172:175], v[180:183], v[50:53]
	v_mfma_f32_16x16x32_bf16 v[42:45], v[164:167], v[212:215], v[42:45]
	v_mfma_f32_16x16x32_bf16 v[34:37], v[172:175], v[212:215], v[34:37]
	v_mfma_f32_16x16x32_bf16 v[26:29], v[164:167], v[220:223], v[26:29]
	v_mfma_f32_16x16x32_bf16 v[18:21], v[172:175], v[220:223], v[18:21]
	v_mfma_f32_16x16x32_bf16 v[10:13], v[164:167], v[228:231], v[10:13]
	v_mfma_f32_16x16x32_bf16 v[2:5], v[172:175], v[228:231], v[2:5]
	v_mfma_f32_16x16x32_bf16 v[58:61], v[168:171], v[208:211], v[58:61]
	v_mfma_f32_16x16x32_bf16 v[50:53], v[176:179], v[208:211], v[50:53]
	v_mfma_f32_16x16x32_bf16 v[42:45], v[168:171], v[216:219], v[42:45]
	v_mfma_f32_16x16x32_bf16 v[34:37], v[176:179], v[216:219], v[34:37]
	v_mfma_f32_16x16x32_bf16 v[26:29], v[168:171], v[224:227], v[26:29]
	v_mfma_f32_16x16x32_bf16 v[18:21], v[176:179], v[224:227], v[18:21]
	v_mfma_f32_16x16x32_bf16 v[10:13], v[168:171], v[232:235], v[10:13]
	v_mfma_f32_16x16x32_bf16 v[2:5], v[176:179], v[232:235], v[2:5]
	s_setprio 0
	s_barrier
	s_add_i32 s55, 0, 0x18000
	v_add_u32_e32 v159, s55, v147
	s_add_i32 s57, 0, 0x1c000
	ds_read_b128 v[140:143], v159
	ds_read_b128 v[150:153], v159 offset:1024
	ds_read_b128 v[154:157], v159 offset:2048
	ds_read_b128 v[160:163], v159 offset:3072
	v_add_u32_e32 v159, s57, v147
	ds_read_b128 v[164:167], v159
	ds_read_b128 v[168:171], v159 offset:1024
	ds_read_b128 v[172:175], v159 offset:2048
	ds_read_b128 v[176:179], v159 offset:3072
	s_add_u32 s34, s34, 0x40000
	s_addc_u32 s35, s35, 0
	s_mov_b32 m0, s45

; #define PG8_STAGE(bufoff, gbase, voff) do { _Pragma("unroll") for (int _i = 0; _i < 2; ++_i) \
;         __builtin_amdgcn_global_load_lds((const unsigned*)((const char*)(gbase) + (voff)[_i]), (LAS unsigned*)(lds + (bufoff) + ldsw + _i * 8192), 16, 0, 0); } while (0)
; #define PG8_LDA(dst, b, h) do { _Pragma("unroll") for (int m = 0; m < 4; ++m) _Pragma("unroll") for (int k = 0; k < 2; ++k) dst[m][k] = *(const LAS bf16x8*)(lds + PG8_SA(b, h) + aoff + m * 2048 + k * 1024); } while (0)
; #define PG8_LDB(dst, b, h) do { _Pragma("unroll") for (int n = 0; n < 2; ++n) _Pragma("unroll") for (int k = 0; k < 2; ++k) dst[n][k] = *(const LAS bf16x8*)(lds + PG8_SB(b, h) + boff + n * 2048 + k * 1024); } while (0)
; #define PG8_SCHED __builtin_amdgcn_sched_barrier(0)
; template <class Epi, class Sched, bool ALIGN_EPI = false, bool SP2 = false>
; __device__ __forceinline__ void gemm_phase(LAS unsigned char* lds, const Gemm g, const Sched& S, const Epi& E, const int tid) {
;     ...
;             PG8_LDB(B0, 1, 0); PG8_LDB(B1, 1, 1); PG8_SCHED; PG8_LDA(At, 1, 0); PG8_STAGE(PG8_SA(0, 1), a2 + hstep, voffA);
	ds_read_b128 v[180:183], v149 offset:32768
	ds_read_b128 v[208:211], v149 offset:33792
	ds_read_b128 v[212:215], v149 offset:34816
	ds_read_b128 v[216:219], v149 offset:35840
	ds_read_b128 v[220:223], v149 offset:36864
	ds_read_b128 v[224:227], v149 offset:37888
	ds_read_b128 v[228:231], v149 offset:38912
	ds_read_b128 v[232:235], v149 offset:39936
	global_load_lds_dwordx4 v134, s[34:35]

; #define PG8_STAGE(bufoff, gbase, voff) do { _Pragma("unroll") for (int _i = 0; _i < 2; ++_i) \
;         __builtin_amdgcn_global_load_lds((const unsigned*)((const char*)(gbase) + (voff)[_i]), (LAS unsigned*)(lds + (bufoff) + ldsw + _i * 8192), 16, 0, 0); } while (0)
; #define PG8_LDA(dst, b, h) do { _Pragma("unroll") for (int m = 0; m < 4; ++m) _Pragma("unroll") for (int k = 0; k < 2; ++k) dst[m][k] = *(const LAS bf16x8*)(lds + PG8_SA(b, h) + aoff + m * 2048 + k * 1024); } while (0)
; #define PG8_MMA(ai, bj, At, Bt) do { __builtin_amdgcn_s_setprio(1); _Pragma("unroll") for (int m = 0; m < 4; ++m) _Pragma("unroll") for (int n = 0; n < 2; ++n) _Pragma("unroll") for (int k = 0; k < 2; ++k) \
;         acc[ai][bj][m][n] = __builtin_amdgcn_mfma_f32_16x16x32_bf16(Bt[n][k], At[m][k], acc[ai][bj][m][n], 0, 0, 0); __builtin_amdgcn_s_setprio(0); } while (0)
; #define PG8_WAIT_V(n) asm volatile("s_waitcnt vmcnt(" #n ")" ::: "memory")
; #define PG8_WAIT_L(n) asm volatile("s_waitcnt lgkmcnt(" #n ")" ::: "memory")
; #define PG8_BAR __builtin_amdgcn_s_barrier()
; #define PG8_SCHED __builtin_amdgcn_sched_barrier(0)
; template <class Epi, class Sched, bool ALIGN_EPI = false, bool SP2 = false>
; __device__ __forceinline__ void gemm_phase(LAS unsigned char* lds, const Gemm g, const Sched& S, const Epi& E, const int tid) {
;     ...
;             PG8_WAIT_V(8); PG8_WAIT_L(0); PG8_BAR; PG8_MMA(0, 0, At, B0); PG8_MMA(0, 1, At, B1); PG8_BAR; PG8_SCHED;
;             PG8_LDA(At, 1, 1); PG8_STAGE(PG8_SB(1, 0), b3, voffB); PG8_STAGE(PG8_SB(1, 1), b3 + hstep, voffB); PG8_STAGE(PG8_SA(1, 0), a3, voffA);
	s_mov_b32 m0, s46
	s_nop 0
	global_load_lds_dwordx4 v132, s[34:35]
	s_waitcnt vmcnt(8)
	s_waitcnt lgkmcnt(0)
	s_barrier
	s_setprio 1
	s_waitcnt lgkmcnt(0)
	v_mfma_f32_16x16x32_bf16 v[126:129], v[140:143], v[180:183], v[126:129]
	v_mfma_f32_16x16x32_bf16 v[118:121], v[154:157], v[180:183], v[118:121]
	v_mfma_f32_16x16x32_bf16 v[110:113], v[140:143], v[212:215], v[110:113]
	v_mfma_f32_16x16x32_bf16 v[102:105], v[154:157], v[212:215], v[102:105]
	v_mfma_f32_16x16x32_bf16 v[94:97], v[140:143], v[220:223], v[94:97]
	v_mfma_f32_16x16x32_bf16 v[86:89], v[154:157], v[220:223], v[86:89]
	v_mfma_f32_16x16x32_bf16 v[78:81], v[140:143], v[228:231], v[78:81]
	v_mfma_f32_16x16x32_bf16 v[70:73], v[154:157], v[228:231], v[70:73]
	v_mfma_f32_16x16x32_bf16 v[126:129], v[150:153], v[208:211], v[126:129]
	v_mfma_f32_16x16x32_bf16 v[118:121], v[160:163], v[208:211], v[118:121]
	v_mfma_f32_16x16x32_bf16 v[110:113], v[150:153], v[216:219], v[110:113]
	v_mfma_f32_16x16x32_bf16 v[102:105], v[160:163], v[216:219], v[102:105]
	v_mfma_f32_16x16x32_bf16 v[94:97], v[150:153], v[224:227], v[94:97]
	v_mfma_f32_16x16x32_bf16 v[86:89], v[160:163], v[224:227], v[86:89]
	v_mfma_f32_16x16x32_bf16 v[78:81], v[150:153], v[232:235], v[78:81]
	v_mfma_f32_16x16x32_bf16 v[70:73], v[160:163], v[232:235], v[70:73]
	s_setprio 0
	s_setprio 1
	v_mfma_f32_16x16x32_bf16 v[122:125], v[164:167], v[180:183], v[122:125]
	v_mfma_f32_16x16x32_bf16 v[114:117], v[172:175], v[180:183], v[114:117]
	v_mfma_f32_16x16x32_bf16 v[106:109], v[164:167], v[212:215], v[106:109]
	v_mfma_f32_16x16x32_bf16 v[98:101], v[172:175], v[212:215], v[98:101]
	v_mfma_f32_16x16x32_bf16 v[90:93], v[164:167], v[220:223], v[90:93]
	v_mfma_f32_16x16x32_bf16 v[82:85], v[172:175], v[220:223], v[82:85]
	v_mfma_f32_16x16x32_bf16 v[74:77], v[164:167], v[228:231], v[74:77]
	v_mfma_f32_16x16x32_bf16 v[66:69], v[172:175], v[228:231], v[66:69]
	v_mfma_f32_16x16x32_bf16 v[122:125], v[168:171], v[208:211], v[122:125]
	v_mfma_f32_16x16x32_bf16 v[114:117], v[176:179], v[208:211], v[114:117]
	v_mfma_f32_16x16x32_bf16 v[106:109], v[168:171], v[216:219], v[106:109]
	v_mfma_f32_16x16x32_bf16 v[98:101], v[176:179], v[216:219], v[98:101]
	v_mfma_f32_16x16x32_bf16 v[90:93], v[168:171], v[224:227], v[90:93]
	v_mfma_f32_16x16x32_bf16 v[82:85], v[176:179], v[224:227], v[82:85]
	v_mfma_f32_16x16x32_bf16 v[74:77], v[168:171], v[232:235], v[74:77]
	v_mfma_f32_16x16x32_bf16 v[66:69], v[176:179], v[232:235], v[66:69]
	s_setprio 0
	s_barrier
	s_add_i32 s34, s55, s40
	v_lshl_add_u64 v[144:145], v[144:145], 0, s[36:37]
	s_mov_b32 m0, s34
	ds_read_b128 v[180:183], v149 offset:49152
	ds_read_b128 v[208:211], v149 offset:50176
	ds_read_b128 v[212:215], v149 offset:51200
	ds_read_b128 v[216:219], v149 offset:52224
	ds_read_b128 v[220:223], v149 offset:53248
	ds_read_b128 v[224:227], v149 offset:54272
	ds_read_b128 v[228:231], v149 offset:55296
	ds_read_b128 v[232:235], v149 offset:56320
	global_load_lds_dwordx4 v[144:145], off
	s_add_i32 m0, s34, 0x2000
	s_add_u32 s30, s30, 0x40080
	v_lshl_add_u64 v[144:145], v[236:237], 0, s[36:37]
	s_addc_u32 s31, s31, 0
	s_add_i32 s34, s57, s40
	global_load_lds_dwordx4 v[144:145], off

; #define PG8_STAGE(bufoff, gbase, voff) do { _Pragma("unroll") for (int _i = 0; _i < 2; ++_i) \
;         __builtin_amdgcn_global_load_lds((const unsigned*)((const char*)(gbase) + (voff)[_i]), (LAS unsigned*)(lds + (bufoff) + ldsw + _i * 8192), 16, 0, 0); } while (0)
; #define PG8_LDA(dst, b, h) do { _Pragma("unroll") for (int m = 0; m < 4; ++m) _Pragma("unroll") for (int k = 0; k < 2; ++k) dst[m][k] = *(const LAS bf16x8*)(lds + PG8_SA(b, h) + aoff + m * 2048 + k * 1024); } while (0)
; template <class Epi, class Sched, bool ALIGN_EPI = false, bool SP2 = false>
; __device__ __forceinline__ void gemm_phase(LAS unsigned char* lds, const Gemm g, const Sched& S, const Epi& E, const int tid) {
;     ...
;             PG8_LDA(At, 1, 1); PG8_STAGE(PG8_SB(1, 0), b3, voffB); PG8_STAGE(PG8_SB(1, 1), b3 + hstep, voffB); PG8_STAGE(PG8_SA(1, 0), a3, voffA);
	s_mov_b32 m0, s34
	s_nop 0
	global_load_lds_dwordx4 v0, s[30:31]

; #define PG8_STAGE(bufoff, gbase, voff) do { _Pragma("unroll") for (int _i = 0; _i < 2; ++_i) \
;         __builtin_amdgcn_global_load_lds((const unsigned*)((const char*)(gbase) + (voff)[_i]), (LAS unsigned*)(lds + (bufoff) + ldsw + _i * 8192), 16, 0, 0); } while (0)
; #define PG8_LDA(dst, b, h) do { _Pragma("unroll") for (int m = 0; m < 4; ++m) _Pragma("unroll") for (int k = 0; k < 2; ++k) dst[m][k] = *(const LAS bf16x8*)(lds + PG8_SA(b, h) + aoff + m * 2048 + k * 1024); } while (0)
; #define PG8_LDB(dst, b, h) do { _Pragma("unroll") for (int n = 0; n < 2; ++n) _Pragma("unroll") for (int k = 0; k < 2; ++k) dst[n][k] = *(const LAS bf16x8*)(lds + PG8_SB(b, h) + boff + n * 2048 + k * 1024); } while (0)
; template <class Epi, class Sched, bool ALIGN_EPI = false, bool SP2 = false>
; __device__ __forceinline__ void gemm_phase(LAS unsigned char* lds, const Gemm g, const Sched& S, const Epi& E, const int tid) {
;     ...
;         for (int t = 0; t < nt; t += 2) {
;             const bool last = (t == nt - 2);
;             const char* a1 = cA + (size_t)(t + 1) * kstep;
;             const char* a2 = last ? nA : cA + (size_t)(t + 2) * kstep; const char* b2 = last ? nB : cB + (size_t)(t + 2) * kstep;
;             const char* a3 = a2 + kstep; const char* b3 = b2 + kstep;
;             if (last && has_next) S.a_ready(nxt);
;             if constexpr (SP2) {
;             PG8_LDB(B0, 0, 0); PG8_LDB(B1, 0, 1); PG8_SCHED; PG8_LDA(At, 0, 0); PG8_STAGE(PG8_SA(1, 1), a1 + hstep, voffA);
;             PG8_WAIT_V(8); PG8_WAIT_L(0); PG8_BAR; PG8_MMA(0, 0, At, B0); PG8_MMA(0, 1, At, B1); PG8_BAR; PG8_SCHED;
;             PG8_LDA(At, 0, 1); PG8_STAGE(PG8_SB(0, 0), b2, voffB); PG8_STAGE(PG8_SB(0, 1), b2 + hstep, voffB); PG8_STAGE(PG8_SA(0, 0), a2, voffA);
;             PG8_WAIT_V(8); PG8_WAIT_L(0); PG8_BAR; PG8_MMA(1, 0, At, B0); PG8_MMA(1, 1, At, B1); PG8_BAR; PG8_SCHED;
;             PG8_LDB(B0, 1, 0); PG8_LDB(B1, 1, 1); PG8_SCHED; PG8_LDA(At, 1, 0); PG8_STAGE(PG8_SA(0, 1), a2 + hstep, voffA);
;             PG8_WAIT_V(8); PG8_WAIT_L(0); PG8_BAR; PG8_MMA(0, 0, At, B0); PG8_MMA(0, 1, At, B1); PG8_BAR; PG8_SCHED;
;             PG8_LDA(At, 1, 1); PG8_STAGE(PG8_SB(1, 0), b3, voffB); PG8_STAGE(PG8_SB(1, 1), b3 + hstep, voffB); PG8_STAGE(PG8_SA(1, 0), a3, voffA);
;             PG8_WAIT_V(8); PG8_WAIT_L(0); PG8_BAR; PG8_MMA(1, 0, At, B0); PG8_MMA(1, 1, At, B1); PG8_BAR; PG8_SCHED;
	s_add_i32 m0, s34, 0x2000
	s_nop 0
	global_load_lds_dwordx4 v130, s[30:31]
	v_lshl_add_u64 v[144:145], v[238:239], 0, s[36:37]
	s_mov_b32 m0, s47
	s_nop 0
	global_load_lds_dwordx4 v[144:145], off
	v_lshl_add_u64 v[144:145], v[240:241], 0, s[36:37]
	s_mov_b32 m0, s48
	s_nop 0
	global_load_lds_dwordx4 v[144:145], off
	s_waitcnt vmcnt(8)
	s_waitcnt lgkmcnt(0)
	s_barrier
	s_setprio 1
	s_waitcnt lgkmcnt(0)
	v_mfma_f32_16x16x32_bf16 v[62:65], v[140:143], v[180:183], v[62:65]
	v_mfma_f32_16x16x32_bf16 v[54:57], v[154:157], v[180:183], v[54:57]
	v_mfma_f32_16x16x32_bf16 v[46:49], v[140:143], v[212:215], v[46:49]
	v_mfma_f32_16x16x32_bf16 v[38:41], v[154:157], v[212:215], v[38:41]
	v_mfma_f32_16x16x32_bf16 v[30:33], v[140:143], v[220:223], v[30:33]
	v_mfma_f32_16x16x32_bf16 v[22:25], v[154:157], v[220:223], v[22:25]
	v_mfma_f32_16x16x32_bf16 v[14:17], v[140:143], v[228:231], v[14:17]
	v_mfma_f32_16x16x32_bf16 v[6:9], v[154:157], v[228:231], v[6:9]
	v_mfma_f32_16x16x32_bf16 v[62:65], v[150:153], v[208:211], v[62:65]
	v_mfma_f32_16x16x32_bf16 v[54:57], v[160:163], v[208:211], v[54:57]
	v_mfma_f32_16x16x32_bf16 v[46:49], v[150:153], v[216:219], v[46:49]
	v_mfma_f32_16x16x32_bf16 v[38:41], v[160:163], v[216:219], v[38:41]
	v_mfma_f32_16x16x32_bf16 v[30:33], v[150:153], v[224:227], v[30:33]
	v_mfma_f32_16x16x32_bf16 v[22:25], v[160:163], v[224:227], v[22:25]
	v_mfma_f32_16x16x32_bf16 v[14:17], v[150:153], v[232:235], v[14:17]
	v_mfma_f32_16x16x32_bf16 v[6:9], v[160:163], v[232:235], v[6:9]
	s_setprio 0
	s_setprio 1
	v_mfma_f32_16x16x32_bf16 v[58:61], v[164:167], v[180:183], v[58:61]
	v_mfma_f32_16x16x32_bf16 v[50:53], v[172:175], v[180:183], v[50:53]
	v_mfma_f32_16x16x32_bf16 v[42:45], v[164:167], v[212:215], v[42:45]
	v_mfma_f32_16x16x32_bf16 v[34:37], v[172:175], v[212:215], v[34:37]
	v_mfma_f32_16x16x32_bf16 v[26:29], v[164:167], v[220:223], v[26:29]
	v_mfma_f32_16x16x32_bf16 v[18:21], v[172:175], v[220:223], v[18:21]
	v_mfma_f32_16x16x32_bf16 v[10:13], v[164:167], v[228:231], v[10:13]
	v_mfma_f32_16x16x32_bf16 v[2:5], v[172:175], v[228:231], v[2:5]
	v_mfma_f32_16x16x32_bf16 v[58:61], v[168:171], v[208:211], v[58:61]
	v_mfma_f32_16x16x32_bf16 v[50:53], v[176:179], v[208:211], v[50:53]
	v_mfma_f32_16x16x32_bf16 v[42:45], v[168:171], v[216:219], v[42:45]
	v_mfma_f32_16x16x32_bf16 v[34:37], v[176:179], v[216:219], v[34:37]
	v_mfma_f32_16x16x32_bf16 v[26:29], v[168:171], v[224:227], v[26:29]
	v_mfma_f32_16x16x32_bf16 v[18:21], v[176:179], v[224:227], v[18:21]
	v_mfma_f32_16x16x32_bf16 v[10:13], v[168:171], v[232:235], v[10:13]
	v_mfma_f32_16x16x32_bf16 v[2:5], v[176:179], v[232:235], v[2:5]
	s_setprio 0
	s_barrier
	s_add_i32 s54, s54, 2
	s_add_u32 s52, s52, 0x100
	s_addc_u32 s53, s53, 0
	s_add_u32 s28, s28, 0x100
	s_addc_u32 s29, s29, 0
	s_cmp_gt_u32 s54, 13
	s_cbranch_scc0 .LBB0_592
	s_and_b64 vcc, exec, s[10:11]
	s_cbranch_vccz .LBB0_595
	s_barrier
